# DSA attention chunk rewritten: key fragments and bias lookups up front, score tiles interleaved, selects skipped for fully valid chunks, row-max DPP chains interleaved, paired bf16 convert, packed run
# speedup vs baseline: 1.0213x; 1.0102x over previous
.LBB0_2489:
	s_waitcnt lgkmcnt(0)
	s_andn2_b64 vcc, exec, s[28:29]
	s_cbranch_vccnz .LBB0_1626
	s_add_i32 s6, s54, s16
	s_ashr_i32 s7, s6, 31
	s_lshl_b64 s[10:11], s[6:7], 12
	v_lshl_add_u64 v[2:3], v[170:171], 0, s[10:11]
	global_load_dwordx4 v[4:7], v[2:3], off
	global_load_dwordx4 v[8:11], v[2:3], off offset:64
	global_load_dwordx4 v[12:15], v[2:3], off offset:128
	global_load_dwordx4 v[16:19], v[2:3], off offset:192
	s_lshl_b32 s16, s16, 8
	v_readfirstlane_b32 s96, v174
	v_readfirstlane_b32 s97, v175
	v_and_b32_e32 v152, 15, v192
	v_lshlrev_b32_e32 v152, 4, v152
	s_nop 1
	s_add_u32 s96, s96, s16
	s_addc_u32 s97, s97, 0
	v_mov_b32_e32 v226, 0x3fb8aa3b
	v_mov_b32_e32 v227, 0x3fb8aa3b
	s_mov_b32 s98, 0x22800
	s_movk_i32 s99, 0x7f
	v_add_u32_e32 v153, 0x20000, v214
	ds_read_b32 v20, v213
	ds_read_b32 v24, v213 offset:16
	ds_read_b32 v28, v213 offset:32
	ds_read_b32 v64, v213 offset:48
	ds_read_b32 v72, v213 offset:64
	ds_read_b32 v80, v213 offset:80
	ds_read_b32 v88, v213 offset:96
	ds_read_b32 v96, v213 offset:112
	ds_read_b32 v68, v213 offset:128
	ds_read_b32 v76, v213 offset:144
	ds_read_b32 v84, v213 offset:160
	ds_read_b32 v92, v213 offset:176
	ds_read_b32 v100, v213 offset:192
	ds_read_b32 v104, v213 offset:208
	ds_read_b32 v108, v213 offset:224
	ds_read_b32 v112, v213 offset:240
	s_waitcnt lgkmcnt(0)
	v_lshl_or_b32 v20, v20, 8, v152
	global_load_dwordx4 v[20:23], v20, s[96:97]
	v_lshl_or_b32 v24, v24, 8, v152
	global_load_dwordx4 v[24:27], v24, s[96:97]
	v_lshl_or_b32 v28, v28, 8, v152
	global_load_dwordx4 v[28:31], v28, s[96:97]
	v_lshl_or_b32 v64, v64, 8, v152
	global_load_dwordx4 v[64:67], v64, s[96:97]
	v_lshl_or_b32 v72, v72, 8, v152
	global_load_dwordx4 v[72:75], v72, s[96:97]
	v_lshl_or_b32 v80, v80, 8, v152
	global_load_dwordx4 v[80:83], v80, s[96:97]
	v_lshl_or_b32 v88, v88, 8, v152
	global_load_dwordx4 v[88:91], v88, s[96:97]
	v_lshl_or_b32 v96, v96, 8, v152
	global_load_dwordx4 v[96:99], v96, s[96:97]
	v_lshl_or_b32 v68, v68, 8, v152
	global_load_dwordx4 v[68:71], v68, s[96:97]
	v_lshl_or_b32 v76, v76, 8, v152
	global_load_dwordx4 v[76:79], v76, s[96:97]
	v_lshl_or_b32 v84, v84, 8, v152
	global_load_dwordx4 v[84:87], v84, s[96:97]
	v_lshl_or_b32 v92, v92, 8, v152
	global_load_dwordx4 v[92:95], v92, s[96:97]
	v_lshl_or_b32 v100, v100, 8, v152
	global_load_dwordx4 v[100:103], v100, s[96:97]
	v_lshl_or_b32 v104, v104, 8, v152
	global_load_dwordx4 v[104:107], v104, s[96:97]
	v_lshl_or_b32 v108, v108, 8, v152
	global_load_dwordx4 v[108:111], v108, s[96:97]
	v_lshl_or_b32 v112, v112, 8, v152
	global_load_dwordx4 v[112:115], v112, s[96:97]
	s_add_i32 s6, s40, 31
	s_ashr_i32 s16, s6, 5
	s_cmp_gt_i32 s16, 0
	s_cbranch_scc0 .LBB0_1624
	v_mov_b32_e32 v2, v1
	v_mov_b32_e32 v3, v1
	v_mov_b32_e32 v0, v1
	v_mov_b32_e32 v154, 0
	v_mov_b64_e32 v[34:35], v[2:3]
	v_mov_b64_e32 v[38:39], v[2:3]
	v_mov_b64_e32 v[42:43], v[2:3]
	v_mov_b64_e32 v[46:47], v[2:3]
	v_mov_b64_e32 v[50:51], v[2:3]
	v_mov_b64_e32 v[54:55], v[2:3]
	v_mov_b64_e32 v[58:59], v[2:3]
	v_mov_b64_e32 v[62:63], v[2:3]
	s_mov_b32 s41, 0
	v_mov_b32_e32 v230, 0xff800000
	s_mov_b32 s55, 3
	s_mov_b32 s57, s42
	v_mov_b64_e32 v[32:33], v[0:1]
	v_mov_b64_e32 v[36:37], v[0:1]
	v_mov_b64_e32 v[40:41], v[0:1]
	v_mov_b64_e32 v[44:45], v[0:1]
	v_mov_b64_e32 v[48:49], v[0:1]
	v_mov_b64_e32 v[52:53], v[0:1]
	v_mov_b64_e32 v[56:57], v[0:1]
	v_mov_b64_e32 v[60:61], v[0:1]
	v_mov_b32_e32 v231, 0xff800000
	v_mov_b32_e32 v232, 0xff800000
	v_mov_b32_e32 v233, 0xff800000
	v_mov_b32_e32 v155, v154
	v_mov_b32_e32 v156, v154
	v_mov_b32_e32 v157, v154
	s_branch .LBB0_2526

.Lat_av_A:
	v_max_f32_e32 v2, v120, v121
	v_max_f32_e32 v3, v122, v123
	v_max_f32_e32 v158, v124, v125
	v_max_f32_e32 v159, v126, v127
	v_max_f32_dpp v2, v2, v2 quad_perm:[1,0,3,2] row_mask:0xf bank_mask:0xf bound_ctrl:1
	v_max_f32_dpp v3, v3, v3 quad_perm:[1,0,3,2] row_mask:0xf bank_mask:0xf bound_ctrl:1
	v_max_f32_dpp v158, v158, v158 quad_perm:[1,0,3,2] row_mask:0xf bank_mask:0xf bound_ctrl:1
	v_max_f32_dpp v159, v159, v159 quad_perm:[1,0,3,2] row_mask:0xf bank_mask:0xf bound_ctrl:1
	v_max_f32_dpp v2, v2, v2 quad_perm:[2,3,0,1] row_mask:0xf bank_mask:0xf bound_ctrl:1
	v_max_f32_dpp v3, v3, v3 quad_perm:[2,3,0,1] row_mask:0xf bank_mask:0xf bound_ctrl:1
	v_max_f32_dpp v158, v158, v158 quad_perm:[2,3,0,1] row_mask:0xf bank_mask:0xf bound_ctrl:1
	v_max_f32_dpp v159, v159, v159 quad_perm:[2,3,0,1] row_mask:0xf bank_mask:0xf bound_ctrl:1
	v_max_f32_dpp v2, v2, v2 row_half_mirror row_mask:0xf bank_mask:0xf bound_ctrl:1
	v_max_f32_dpp v3, v3, v3 row_half_mirror row_mask:0xf bank_mask:0xf bound_ctrl:1
	v_max_f32_dpp v158, v158, v158 row_half_mirror row_mask:0xf bank_mask:0xf bound_ctrl:1
	v_max_f32_dpp v159, v159, v159 row_half_mirror row_mask:0xf bank_mask:0xf bound_ctrl:1
	v_mov_b32_dpp v128, v2 row_mirror row_mask:0xf bank_mask:0xf bound_ctrl:1
	v_mov_b32_dpp v129, v3 row_mirror row_mask:0xf bank_mask:0xf bound_ctrl:1
	v_mov_b32_dpp v130, v158 row_mirror row_mask:0xf bank_mask:0xf bound_ctrl:1
	v_mov_b32_dpp v131, v159 row_mirror row_mask:0xf bank_mask:0xf bound_ctrl:1
	v_max3_f32 v239, v233, v2, v128
	v_max3_f32 v238, v232, v3, v129
	v_max3_f32 v151, v231, v158, v130
	v_max3_f32 v150, v230, v159, v131
	v_sub_f32_e32 v161, v233, v239
	v_sub_f32_e32 v160, v232, v238
	v_sub_f32_e32 v185, v231, v151
	v_sub_f32_e32 v184, v230, v150
	v_sub_f32_e32 v120, v120, v239
	v_sub_f32_e32 v121, v121, v239
	v_sub_f32_e32 v122, v122, v238
	v_sub_f32_e32 v123, v123, v238
	v_sub_f32_e32 v124, v124, v151
	v_sub_f32_e32 v125, v125, v151
	v_sub_f32_e32 v126, v126, v150
	v_sub_f32_e32 v127, v127, v150
	v_mov_b32_e32 v233, v239
	v_mov_b32_e32 v232, v238
	v_mov_b32_e32 v231, v151
	v_mov_b32_e32 v230, v150
	v_mul_f32_e32 v120, 0x3fb8aa3b, v120
	v_mul_f32_e32 v121, 0x3fb8aa3b, v121
	v_mul_f32_e32 v122, 0x3fb8aa3b, v122
	v_mul_f32_e32 v123, 0x3fb8aa3b, v123
	v_mul_f32_e32 v124, 0x3fb8aa3b, v124
	v_mul_f32_e32 v125, 0x3fb8aa3b, v125
	v_mul_f32_e32 v126, 0x3fb8aa3b, v126
	v_mul_f32_e32 v127, 0x3fb8aa3b, v127
	v_mul_f32_e32 v160, 0x3fb8aa3b, v160
	v_mul_f32_e32 v161, 0x3fb8aa3b, v161
	v_mul_f32_e32 v184, 0x3fb8aa3b, v184
	v_mul_f32_e32 v185, 0x3fb8aa3b, v185
	v_exp_f32_e32 v3, v120
	v_exp_f32_e32 v159, v121
	v_exp_f32_e32 v2, v122
	v_exp_f32_e32 v158, v123
	v_exp_f32_e32 v181, v124
	v_exp_f32_e32 v183, v125
	v_exp_f32_e32 v180, v126
	v_exp_f32_e32 v182, v127
	v_exp_f32_e32 v161, v161
	v_exp_f32_e32 v160, v160
	v_exp_f32_e32 v185, v185
	v_exp_f32_e32 v184, v184
	v_cvt_pk_bf16_f32 v128, v3, v159
	v_cvt_pk_bf16_f32 v129, v2, v158
	v_cvt_pk_bf16_f32 v130, v181, v183
	v_cvt_pk_bf16_f32 v131, v180, v182
	ds_write_b16 v221, v128 offset:8704
	ds_write_b16_d16_hi v221, v128 offset:8736
	ds_write_b16 v221, v129 offset:8784
	ds_write_b16_d16_hi v221, v129 offset:8816
	ds_write_b16 v221, v130 offset:8864
	ds_write_b16_d16_hi v221, v130 offset:8896
	ds_write_b16 v221, v131 offset:8944
	ds_write_b16_d16_hi v221, v131 offset:8976
	v_min3_f32 v0, v161, v160, v185
	v_min_f32_e32 v0, v0, v184
	s_waitcnt lgkmcnt(0)
	ds_read_b128 v[116:119], v222 offset:8704
	ds_read_b64_tr_b16 v[148:149], v193 offset:0
	ds_read_b64_tr_b16 v[150:151], v193 offset:1088
	ds_read_b64_tr_b16 v[144:145], v193 offset:32
	ds_read_b64_tr_b16 v[146:147], v193 offset:1120
	ds_read_b64_tr_b16 v[140:141], v193 offset:64
	ds_read_b64_tr_b16 v[142:143], v193 offset:1152
	ds_read_b64_tr_b16 v[136:137], v193 offset:96
	ds_read_b64_tr_b16 v[138:139], v193 offset:1184
	ds_read_b64_tr_b16 v[132:133], v193 offset:128
	ds_read_b64_tr_b16 v[134:135], v193 offset:1216
	ds_read_b64_tr_b16 v[128:129], v193 offset:160
	ds_read_b64_tr_b16 v[130:131], v193 offset:1248
	ds_read_b64_tr_b16 v[124:125], v193 offset:192
	ds_read_b64_tr_b16 v[126:127], v193 offset:1280
	ds_read_b64_tr_b16 v[120:121], v193 offset:224
	ds_read_b64_tr_b16 v[122:123], v193 offset:1312
	v_cmp_neq_f32_e32 vcc, 1.0, v0
	s_cbranch_vccz .Lat_nr_A
	v_pk_mul_f32 v[60:61], v[60:61], v[160:161] op_sel:[0,1] op_sel_hi:[1,0]
	v_pk_mul_f32 v[62:63], v[62:63], v[184:185] op_sel:[0,1] op_sel_hi:[1,0]
	v_pk_mul_f32 v[56:57], v[56:57], v[160:161] op_sel:[0,1] op_sel_hi:[1,0]
	v_pk_mul_f32 v[58:59], v[58:59], v[184:185] op_sel:[0,1] op_sel_hi:[1,0]
	v_pk_mul_f32 v[52:53], v[52:53], v[160:161] op_sel:[0,1] op_sel_hi:[1,0]
	v_pk_mul_f32 v[54:55], v[54:55], v[184:185] op_sel:[0,1] op_sel_hi:[1,0]
	v_pk_mul_f32 v[48:49], v[48:49], v[160:161] op_sel:[0,1] op_sel_hi:[1,0]
	v_pk_mul_f32 v[50:51], v[50:51], v[184:185] op_sel:[0,1] op_sel_hi:[1,0]
	v_pk_mul_f32 v[44:45], v[44:45], v[160:161] op_sel:[0,1] op_sel_hi:[1,0]
	v_pk_mul_f32 v[46:47], v[46:47], v[184:185] op_sel:[0,1] op_sel_hi:[1,0]
	v_pk_mul_f32 v[40:41], v[40:41], v[160:161] op_sel:[0,1] op_sel_hi:[1,0]
	v_pk_mul_f32 v[42:43], v[42:43], v[184:185] op_sel:[0,1] op_sel_hi:[1,0]
	v_pk_mul_f32 v[36:37], v[36:37], v[160:161] op_sel:[0,1] op_sel_hi:[1,0]
	v_pk_mul_f32 v[38:39], v[38:39], v[184:185] op_sel:[0,1] op_sel_hi:[1,0]
	v_pk_mul_f32 v[32:33], v[32:33], v[160:161] op_sel:[0,1] op_sel_hi:[1,0]
	v_pk_mul_f32 v[34:35], v[34:35], v[184:185] op_sel:[0,1] op_sel_hi:[1,0]
